# prep S5 kernel loop re-associated; s_nop padding keeps the following code at the earlier 256-byte placement
# speedup vs baseline: 1.0296x; 1.0296x over previous
.LBB0_30:
	global_load_dword v75, v[66:67], off
	global_load_dword v76, v[68:69], off
	global_load_dword v77, v[70:71], off
	global_load_dword v78, v[72:73], off
	v_and_b32_e32 v79, 0x7e, v0
	s_add_i32 s14, 0, 0x10200
	v_lshl_or_b32 v80, v0, 2, 4
	v_lshl_add_u32 v79, v79, 2, s14
	v_add_u32_e32 v80, s14, v80
	ds_read_b32 v79, v79
	ds_read_b32 v80, v80
	v_add_co_u32_e32 v64, vcc, 0x200, v64
	s_xor_b64 s[14:15], vcc, -1
	s_and_b64 s[14:15], exec, s[14:15]
	v_add_u32_e32 v0, 64, v0
	v_lshl_add_u64 v[66:67], v[66:67], 0, s[44:45]
	v_lshl_add_u64 v[68:69], v[68:69], 0, s[44:45]
	v_lshl_add_u64 v[70:71], v[70:71], 0, s[44:45]
	v_lshl_add_u64 v[72:73], v[72:73], 0, s[44:45]
	s_or_b64 s[0:1], s[14:15], s[0:1]
	s_waitcnt vmcnt(2) lgkmcnt(0)
	v_mul_f32_e32 v81, v76, v80
	v_mul_f32_e32 v80, v75, v80
	v_fma_f32 v75, v75, v79, -v81
	v_fmac_f32_e32 v80, v76, v79
	s_waitcnt vmcnt(0)
	ds_write2st64_b32 v74, v77, v78 offset0:32 offset1:48
	ds_write2st64_b32 v74, v75, v80 offset1:16
	v_add_u32_e32 v74, 0x800, v74
	s_andn2_b64 exec, exec, s[0:1]
	s_cbranch_execnz .LBB0_30
	s_or_b64 exec, exec, s[0:1]
	s_ashr_i32 s64, s62, 5
	s_and_b32 s43, s62, 31
	s_lshl_b32 s0, s64, 9
	s_lshl_b32 s1, s43, 4
	s_or_b32 s46, s1, s0
	s_mov_b64 s[0:1], 0
	v_mov_b32_e32 v0, v88
	v_mov_b32_e32 v64, v173
	s_waitcnt lgkmcnt(0)
	s_barrier
	ds_read_b128 v[100:103], v90 offset:0
	ds_read_b128 v[104:107], v90 offset:16
	ds_read_b128 v[108:111], v90 offset:4096
	ds_read_b128 v[112:115], v90 offset:4112
	v_add_u32_e32 v78, 0, v89
	v_add_u32_e32 v79, 0x1000, v78
	ds_read2_b32 v[116:117], v78 offset0:0 offset1:16
	ds_read2_b32 v[118:119], v78 offset0:32 offset1:48
	ds_read2_b32 v[120:121], v78 offset0:64 offset1:80
	ds_read2_b32 v[122:123], v78 offset0:96 offset1:112
	ds_read2_b32 v[70:71], v79 offset0:0 offset1:16
	ds_read2_b32 v[72:73], v79 offset0:32 offset1:48
	ds_read2_b32 v[74:75], v79 offset0:64 offset1:80
	ds_read2_b32 v[76:77], v79 offset0:96 offset1:112
	s_waitcnt lgkmcnt(0)
	v_mul_f32_e32 v66, v108, v70
	v_mul_f32_e32 v68, v100, v70
	v_fma_f32 v124, v100, v116, -v66
	v_fma_f32 v125, v108, v116, v68
	v_mul_f32_e32 v66, v109, v71
	v_mul_f32_e32 v68, v101, v71
	v_fma_f32 v126, v101, v117, -v66
	v_fma_f32 v127, v109, v117, v68
	v_mul_f32_e32 v66, v110, v72
	v_mul_f32_e32 v68, v102, v72
	v_fma_f32 v128, v102, v118, -v66
	v_fma_f32 v129, v110, v118, v68
	v_mul_f32_e32 v66, v111, v73
	v_mul_f32_e32 v68, v103, v73
	v_fma_f32 v130, v103, v119, -v66
	v_fma_f32 v131, v111, v119, v68
	v_mul_f32_e32 v66, v112, v74
	v_mul_f32_e32 v68, v104, v74
	v_fma_f32 v132, v104, v120, -v66
	v_fma_f32 v133, v112, v120, v68
	v_mul_f32_e32 v66, v113, v75
	v_mul_f32_e32 v68, v105, v75
	v_fma_f32 v134, v105, v121, -v66
	v_fma_f32 v135, v113, v121, v68
	v_mul_f32_e32 v66, v114, v76
	v_mul_f32_e32 v68, v106, v76
	v_fma_f32 v136, v106, v122, -v66
	v_fma_f32 v137, v114, v122, v68
	v_mul_f32_e32 v66, v115, v77
	v_mul_f32_e32 v68, v107, v77
	v_fma_f32 v138, v107, v123, -v66
	v_fma_f32 v139, v115, v123, v68
	ds_read_b128 v[100:103], v90 offset:32
	ds_read_b128 v[104:107], v90 offset:48
	ds_read_b128 v[108:111], v90 offset:4128
	ds_read_b128 v[112:115], v90 offset:4144
	v_add_u32_e32 v78, 0x200, v89
	v_add_u32_e32 v79, 0x1000, v78
	ds_read2_b32 v[116:117], v78 offset0:0 offset1:16
	ds_read2_b32 v[118:119], v78 offset0:32 offset1:48
	ds_read2_b32 v[120:121], v78 offset0:64 offset1:80
	ds_read2_b32 v[122:123], v78 offset0:96 offset1:112
	ds_read2_b32 v[70:71], v79 offset0:0 offset1:16
	ds_read2_b32 v[72:73], v79 offset0:32 offset1:48
	ds_read2_b32 v[74:75], v79 offset0:64 offset1:80
	ds_read2_b32 v[76:77], v79 offset0:96 offset1:112
	s_waitcnt lgkmcnt(0)
	v_mul_f32_e32 v66, v108, v70
	v_mul_f32_e32 v68, v100, v70
	v_fma_f32 v140, v100, v116, -v66
	v_fma_f32 v141, v108, v116, v68
	v_mul_f32_e32 v66, v109, v71
	v_mul_f32_e32 v68, v101, v71
	v_fma_f32 v142, v101, v117, -v66
	v_fma_f32 v143, v109, v117, v68
	v_mul_f32_e32 v66, v110, v72
	v_mul_f32_e32 v68, v102, v72
	v_fma_f32 v144, v102, v118, -v66
	v_fma_f32 v145, v110, v118, v68
	v_mul_f32_e32 v66, v111, v73
	v_mul_f32_e32 v68, v103, v73
	v_fma_f32 v146, v103, v119, -v66
	v_fma_f32 v147, v111, v119, v68
	v_mul_f32_e32 v66, v112, v74
	v_mul_f32_e32 v68, v104, v74
	v_fma_f32 v148, v104, v120, -v66
	v_fma_f32 v149, v112, v120, v68
	v_mul_f32_e32 v66, v113, v75
	v_mul_f32_e32 v68, v105, v75
	v_fma_f32 v150, v105, v121, -v66
	v_fma_f32 v151, v113, v121, v68
	v_mul_f32_e32 v66, v114, v76
	v_mul_f32_e32 v68, v106, v76
	v_fma_f32 v152, v106, v122, -v66
	v_fma_f32 v80, v114, v122, v68
	v_mul_f32_e32 v66, v115, v77
	v_mul_f32_e32 v68, v107, v77
	v_fma_f32 v154, v107, v123, -v66
	v_fma_f32 v155, v115, v123, v68
	ds_read_b128 v[100:103], v90 offset:64
	ds_read_b128 v[104:107], v90 offset:80
	ds_read_b128 v[108:111], v90 offset:4160
	ds_read_b128 v[112:115], v90 offset:4176
	v_add_u32_e32 v78, 0x400, v89
	v_add_u32_e32 v79, 0x1000, v78
	ds_read2_b32 v[116:117], v78 offset0:0 offset1:16
	ds_read2_b32 v[118:119], v78 offset0:32 offset1:48
	ds_read2_b32 v[120:121], v78 offset0:64 offset1:80
	ds_read2_b32 v[122:123], v78 offset0:96 offset1:112
	ds_read2_b32 v[70:71], v79 offset0:0 offset1:16
	ds_read2_b32 v[72:73], v79 offset0:32 offset1:48
	ds_read2_b32 v[74:75], v79 offset0:64 offset1:80
	ds_read2_b32 v[76:77], v79 offset0:96 offset1:112
	s_waitcnt lgkmcnt(0)
	v_mul_f32_e32 v66, v108, v70
	v_mul_f32_e32 v68, v100, v70
	v_fma_f32 v156, v100, v116, -v66
	v_fma_f32 v157, v108, v116, v68
	v_mul_f32_e32 v66, v109, v71
	v_mul_f32_e32 v68, v101, v71
	v_fma_f32 v158, v101, v117, -v66
	v_fma_f32 v159, v109, v117, v68
	v_mul_f32_e32 v66, v110, v72
	v_mul_f32_e32 v68, v102, v72
	v_fma_f32 v160, v102, v118, -v66
	v_fma_f32 v161, v110, v118, v68
	v_mul_f32_e32 v66, v111, v73
	v_mul_f32_e32 v68, v103, v73
	v_fma_f32 v162, v103, v119, -v66
	v_fma_f32 v163, v111, v119, v68
	v_mul_f32_e32 v66, v112, v74
	v_mul_f32_e32 v68, v104, v74
	v_fma_f32 v164, v104, v120, -v66
	v_fma_f32 v165, v112, v120, v68
	v_mul_f32_e32 v66, v113, v75
	v_mul_f32_e32 v68, v105, v75
	v_fma_f32 v166, v105, v121, -v66
	v_fma_f32 v167, v113, v121, v68
	v_mul_f32_e32 v66, v114, v76
	v_mul_f32_e32 v68, v106, v76
	v_fma_f32 v168, v106, v122, -v66
	v_fma_f32 v169, v114, v122, v68
	v_mul_f32_e32 v66, v115, v77
	v_mul_f32_e32 v68, v107, v77
	v_fma_f32 v170, v107, v123, -v66
	v_fma_f32 v171, v115, v123, v68
	ds_read_b128 v[100:103], v90 offset:96
	ds_read_b128 v[104:107], v90 offset:112
	ds_read_b128 v[108:111], v90 offset:4192
	ds_read_b128 v[112:115], v90 offset:4208
	v_add_u32_e32 v78, 0x600, v89
	v_add_u32_e32 v79, 0x1000, v78
	ds_read2_b32 v[116:117], v78 offset0:0 offset1:16
	ds_read2_b32 v[118:119], v78 offset0:32 offset1:48
	ds_read2_b32 v[120:121], v78 offset0:64 offset1:80
	ds_read2_b32 v[122:123], v78 offset0:96 offset1:112
	ds_read2_b32 v[70:71], v79 offset0:0 offset1:16
	ds_read2_b32 v[72:73], v79 offset0:32 offset1:48
	ds_read2_b32 v[74:75], v79 offset0:64 offset1:80
	ds_read2_b32 v[76:77], v79 offset0:96 offset1:112
	s_waitcnt lgkmcnt(0)
	v_mul_f32_e32 v66, v108, v70
	v_mul_f32_e32 v68, v100, v70
	v_fma_f32 v172, v100, v116, -v66
	v_fma_f32 v81, v108, v116, v68
	v_mul_f32_e32 v66, v109, v71
	v_mul_f32_e32 v68, v101, v71
	v_fma_f32 v174, v101, v117, -v66
	v_fma_f32 v175, v109, v117, v68
	v_mul_f32_e32 v66, v110, v72
	v_mul_f32_e32 v68, v102, v72
	v_fma_f32 v176, v102, v118, -v66
	v_fma_f32 v177, v110, v118, v68
	v_mul_f32_e32 v66, v111, v73
	v_mul_f32_e32 v68, v103, v73
	v_fma_f32 v178, v103, v119, -v66
	v_fma_f32 v179, v111, v119, v68
	v_mul_f32_e32 v66, v112, v74
	v_mul_f32_e32 v68, v104, v74
	v_fma_f32 v180, v104, v120, -v66
	v_fma_f32 v181, v112, v120, v68
	v_mul_f32_e32 v66, v113, v75
	v_mul_f32_e32 v68, v105, v75
	v_fma_f32 v182, v105, v121, -v66
	v_fma_f32 v183, v113, v121, v68
	v_mul_f32_e32 v66, v114, v76
	v_mul_f32_e32 v68, v106, v76
	v_fma_f32 v184, v106, v122, -v66
	v_fma_f32 v185, v114, v122, v68
	v_mul_f32_e32 v66, v115, v77
	v_mul_f32_e32 v68, v107, v77
	v_fma_f32 v186, v107, v123, -v66
	v_fma_f32 v187, v115, v123, v68
	ds_read_b128 v[100:103], v90 offset:128
	ds_read_b128 v[104:107], v90 offset:144
	ds_read_b128 v[108:111], v90 offset:4224
	ds_read_b128 v[112:115], v90 offset:4240
	v_add_u32_e32 v78, 0x800, v89
	v_add_u32_e32 v79, 0x1000, v78
	ds_read2_b32 v[116:117], v78 offset0:0 offset1:16
	ds_read2_b32 v[118:119], v78 offset0:32 offset1:48
	ds_read2_b32 v[120:121], v78 offset0:64 offset1:80
	ds_read2_b32 v[122:123], v78 offset0:96 offset1:112
	ds_read2_b32 v[70:71], v79 offset0:0 offset1:16
	ds_read2_b32 v[72:73], v79 offset0:32 offset1:48
	ds_read2_b32 v[74:75], v79 offset0:64 offset1:80
	ds_read2_b32 v[76:77], v79 offset0:96 offset1:112
	s_waitcnt lgkmcnt(0)
	v_mul_f32_e32 v66, v108, v70
	v_mul_f32_e32 v68, v100, v70
	v_fma_f32 v188, v100, v116, -v66
	v_fma_f32 v189, v108, v116, v68
	v_mul_f32_e32 v66, v109, v71
	v_mul_f32_e32 v68, v101, v71
	v_fma_f32 v190, v101, v117, -v66
	v_fma_f32 v191, v109, v117, v68
	v_mul_f32_e32 v66, v110, v72
	v_mul_f32_e32 v68, v102, v72
	v_fma_f32 v192, v102, v118, -v66
	v_fma_f32 v193, v110, v118, v68
	v_mul_f32_e32 v66, v111, v73
	v_mul_f32_e32 v68, v103, v73
	v_fma_f32 v194, v103, v119, -v66
	v_fma_f32 v195, v111, v119, v68
	v_mul_f32_e32 v66, v112, v74
	v_mul_f32_e32 v68, v104, v74
	v_fma_f32 v196, v104, v120, -v66
	v_fma_f32 v197, v112, v120, v68
	v_mul_f32_e32 v66, v113, v75
	v_mul_f32_e32 v68, v105, v75
	v_fma_f32 v198, v105, v121, -v66
	v_fma_f32 v199, v113, v121, v68
	v_mul_f32_e32 v66, v114, v76
	v_mul_f32_e32 v68, v106, v76
	v_fma_f32 v200, v106, v122, -v66
	v_fma_f32 v201, v114, v122, v68
	v_mul_f32_e32 v66, v115, v77
	v_mul_f32_e32 v68, v107, v77
	v_fma_f32 v202, v107, v123, -v66
	v_fma_f32 v203, v115, v123, v68
	ds_read_b128 v[100:103], v90 offset:160
	ds_read_b128 v[104:107], v90 offset:176
	ds_read_b128 v[108:111], v90 offset:4256
	ds_read_b128 v[112:115], v90 offset:4272
	v_add_u32_e32 v78, 0xa00, v89
	v_add_u32_e32 v79, 0x1000, v78
	ds_read2_b32 v[116:117], v78 offset0:0 offset1:16
	ds_read2_b32 v[118:119], v78 offset0:32 offset1:48
	ds_read2_b32 v[120:121], v78 offset0:64 offset1:80
	ds_read2_b32 v[122:123], v78 offset0:96 offset1:112
	ds_read2_b32 v[70:71], v79 offset0:0 offset1:16
	ds_read2_b32 v[72:73], v79 offset0:32 offset1:48
	ds_read2_b32 v[74:75], v79 offset0:64 offset1:80
	ds_read2_b32 v[76:77], v79 offset0:96 offset1:112
	s_waitcnt lgkmcnt(0)
	v_mul_f32_e32 v66, v108, v70
	v_mul_f32_e32 v68, v100, v70
	v_fma_f32 v204, v100, v116, -v66
	v_fma_f32 v205, v108, v116, v68
	v_mul_f32_e32 v66, v109, v71
	v_mul_f32_e32 v68, v101, v71
	v_fma_f32 v206, v101, v117, -v66
	v_fma_f32 v207, v109, v117, v68
	v_mul_f32_e32 v66, v110, v72
	v_mul_f32_e32 v68, v102, v72
	v_fma_f32 v208, v102, v118, -v66
	v_fma_f32 v209, v110, v118, v68
	v_mul_f32_e32 v66, v111, v73
	v_mul_f32_e32 v68, v103, v73
	v_fma_f32 v210, v103, v119, -v66
	v_fma_f32 v211, v111, v119, v68
	v_mul_f32_e32 v66, v112, v74
	v_mul_f32_e32 v68, v104, v74
	v_fma_f32 v212, v104, v120, -v66
	v_fma_f32 v213, v112, v120, v68
	v_mul_f32_e32 v66, v113, v75
	v_mul_f32_e32 v68, v105, v75
	v_fma_f32 v214, v105, v121, -v66
	v_fma_f32 v215, v113, v121, v68
	v_mul_f32_e32 v66, v114, v76
	v_mul_f32_e32 v68, v106, v76
	v_fma_f32 v216, v106, v122, -v66
	v_fma_f32 v217, v114, v122, v68
	v_mul_f32_e32 v66, v115, v77
	v_mul_f32_e32 v68, v107, v77
	v_fma_f32 v218, v107, v123, -v66
	v_fma_f32 v219, v115, v123, v68
	ds_read_b128 v[100:103], v90 offset:192
	ds_read_b128 v[104:107], v90 offset:208
	ds_read_b128 v[108:111], v90 offset:4288
	ds_read_b128 v[112:115], v90 offset:4304
	v_add_u32_e32 v78, 0xc00, v89
	v_add_u32_e32 v79, 0x1000, v78
	ds_read2_b32 v[116:117], v78 offset0:0 offset1:16
	ds_read2_b32 v[118:119], v78 offset0:32 offset1:48
	ds_read2_b32 v[120:121], v78 offset0:64 offset1:80
	ds_read2_b32 v[122:123], v78 offset0:96 offset1:112
	ds_read2_b32 v[70:71], v79 offset0:0 offset1:16
	ds_read2_b32 v[72:73], v79 offset0:32 offset1:48
	ds_read2_b32 v[74:75], v79 offset0:64 offset1:80
	ds_read2_b32 v[76:77], v79 offset0:96 offset1:112
	s_waitcnt lgkmcnt(0)
	v_mul_f32_e32 v66, v108, v70
	v_mul_f32_e32 v68, v100, v70
	v_fma_f32 v220, v100, v116, -v66
	v_fma_f32 v221, v108, v116, v68
	v_mul_f32_e32 v66, v109, v71
	v_mul_f32_e32 v68, v101, v71
	v_fma_f32 v222, v101, v117, -v66
	v_fma_f32 v223, v109, v117, v68
	v_mul_f32_e32 v66, v110, v72
	v_mul_f32_e32 v68, v102, v72
	v_fma_f32 v224, v102, v118, -v66
	v_fma_f32 v225, v110, v118, v68
	v_mul_f32_e32 v66, v111, v73
	v_mul_f32_e32 v68, v103, v73
	v_fma_f32 v226, v103, v119, -v66
	v_fma_f32 v227, v111, v119, v68
	v_mul_f32_e32 v66, v112, v74
	v_mul_f32_e32 v68, v104, v74
	v_fma_f32 v228, v104, v120, -v66
	v_fma_f32 v229, v112, v120, v68
	v_mul_f32_e32 v66, v113, v75
	v_mul_f32_e32 v68, v105, v75
	v_fma_f32 v230, v105, v121, -v66
	v_fma_f32 v231, v113, v121, v68
	v_mul_f32_e32 v66, v114, v76
	v_mul_f32_e32 v68, v106, v76
	v_fma_f32 v232, v106, v122, -v66
	v_fma_f32 v233, v114, v122, v68
	v_mul_f32_e32 v66, v115, v77
	v_mul_f32_e32 v68, v107, v77
	v_fma_f32 v234, v107, v123, -v66
	v_fma_f32 v235, v115, v123, v68
	ds_read_b128 v[100:103], v90 offset:224
	ds_read_b128 v[104:107], v90 offset:240
	ds_read_b128 v[108:111], v90 offset:4320
	ds_read_b128 v[112:115], v90 offset:4336
	v_add_u32_e32 v78, 0xe00, v89
	v_add_u32_e32 v79, 0x1000, v78
	ds_read2_b32 v[116:117], v78 offset0:0 offset1:16
	ds_read2_b32 v[118:119], v78 offset0:32 offset1:48
	ds_read2_b32 v[120:121], v78 offset0:64 offset1:80
	ds_read2_b32 v[122:123], v78 offset0:96 offset1:112
	ds_read2_b32 v[70:71], v79 offset0:0 offset1:16
	ds_read2_b32 v[72:73], v79 offset0:32 offset1:48
	ds_read2_b32 v[74:75], v79 offset0:64 offset1:80
	ds_read2_b32 v[76:77], v79 offset0:96 offset1:112
	s_waitcnt lgkmcnt(0)
	v_mul_f32_e32 v66, v108, v70
	v_mul_f32_e32 v68, v100, v70
	v_fma_f32 v236, v100, v116, -v66
	v_fma_f32 v237, v108, v116, v68
	v_mul_f32_e32 v66, v109, v71
	v_mul_f32_e32 v68, v101, v71
	v_fma_f32 v238, v101, v117, -v66
	v_fma_f32 v239, v109, v117, v68
	v_mul_f32_e32 v66, v110, v72
	v_mul_f32_e32 v68, v102, v72
	v_fma_f32 v240, v102, v118, -v66
	v_fma_f32 v241, v110, v118, v68
	v_mul_f32_e32 v66, v111, v73
	v_mul_f32_e32 v68, v103, v73
	v_fma_f32 v242, v103, v119, -v66
	v_fma_f32 v243, v111, v119, v68
	v_mul_f32_e32 v66, v112, v74
	v_mul_f32_e32 v68, v104, v74
	v_fma_f32 v244, v104, v120, -v66
	v_fma_f32 v245, v112, v120, v68
	v_mul_f32_e32 v66, v113, v75
	v_mul_f32_e32 v68, v105, v75
	v_fma_f32 v246, v105, v121, -v66
	v_fma_f32 v247, v113, v121, v68
	v_mul_f32_e32 v66, v114, v76
	v_mul_f32_e32 v68, v106, v76
	v_fma_f32 v248, v106, v122, -v66
	v_fma_f32 v249, v114, v122, v68
	v_mul_f32_e32 v66, v115, v77
	v_mul_f32_e32 v68, v107, v77
	v_fma_f32 v250, v107, v123, -v66
	v_fma_f32 v251, v115, v123, v68
	s_nop 0
	s_nop 0
	s_nop 0
	s_nop 0
	s_nop 0
	s_nop 0
	s_nop 0
	s_nop 0
	s_nop 0
	s_nop 0
	s_nop 0
	s_nop 0
	s_nop 0
	s_nop 0
	s_nop 0
	s_nop 0
	s_nop 0
	s_nop 0
	s_nop 0
	s_nop 0
	s_nop 0
	s_nop 0
	s_nop 0
	s_nop 0
	s_nop 0
	s_nop 0
	s_nop 0
	s_nop 0
	s_nop 0
	s_nop 0
	s_nop 0
	s_nop 0
	s_nop 0
	s_nop 0
	s_nop 0
	s_nop 0
	s_nop 0
	s_nop 0
	s_nop 0
	s_nop 0
	s_nop 0
	s_nop 0
	s_branch .LBB0_33
